# speedup vs baseline: 1.0062x; 1.0062x over previous
; #define LAS __attribute__((address_space(3)))
; __device__ __forceinline__ int opaque_tid(int wid_s) { int l = __builtin_amdgcn_mbcnt_hi(~0u, __builtin_amdgcn_mbcnt_lo(~0u, 0u)); asm volatile("" : "+v"(l)); return (wid_s << 6) | l; }
; __device__ __forceinline__ unsigned cvt_pk_bf16(float lo, float hi) { return __builtin_bit_cast(unsigned, __builtin_amdgcn_cvt_pkrtz(lo, hi)); }
; __host__ __device__ __forceinline__ int in_logical_pn(int j) { return (j < 6) ? j : (j < 8 ? j + 2 : j - 2); }
; #define bx (opaque_bx())
; __device__ __forceinline__ void prep_load(const PrepTask& T, f32x4 (&r)[8], int tid) {
;     const int w = tid >> 6, s4 = tid & 63; const int col = colmap(T.kind, T.kind == KIND_IN ? in_logical_pn(T.pn) : T.pn, 4 * s4);
; #pragma unroll
;     for (int i = 0; i < 8; ++i) r[i] = __builtin_nontemporal_load((const f32x4*)(T.src + (size_t)(T.k0 + 8 * w + i) * T.Nnat + col));
; }
; __device__ __forceinline__ void phase_prep(int wid_s, const Args& a, unsigned char* shm) {
;     const int tid = opaque_tid(wid_s), G = gridDim.x, bx = blockIdx.x;
;     float* Ts = (float*)shm;
;     {
;         LAS unsigned* Lp = (LAS unsigned*)shm;
;         f32x4 r[8]; int j = 0; int t = bx * 4; PrepTask T;
;         if (t < PT_TOTAL) { T = prep_decode(a, t); prep_load(T, r, tid); }
;         while (t < PT_TOTAL) {
;             { const int w = tid >> 6, s4 = tid & 63;
; #pragma unroll
;               for (int q = 0; q < 4; ++q) { const u32x4 pc = {cvt_pk_bf16(r[0][q], r[1][q]), cvt_pk_bf16(r[2][q], r[3][q]), cvt_pk_bf16(r[4][q], r[5][q]), cvt_pk_bf16(r[6][q], r[7][q])};
;                   *(LAS u32x4*)(Lp + (4 * s4 + q) * 36 + 4 * w) = pc; } }
;             __syncthreads();
;             const PrepTask C = T; ++j; const int tn = ((j >> 2) * G + bx) * 4 + (j & 3);
;             if (tn < PT_TOTAL) { T = prep_decode(a, tn); prep_load(T, r, tid); }
; #pragma unroll
;             for (int q = 0; q < 4; ++q) { const int row = q * 64 + (tid >> 3), pc = tid & 7;
;                 const u32x4 v = *(const LAS u32x4*)(Lp + row * 36 + 4 * pc);
;                 *(u32x4*)(C.dst + (size_t)(256 * C.pn + row) * C.K + C.k0 + 8 * pc) = v; }
;             __syncthreads();
;             t = tn;
.LBB0_808:
	s_waitcnt vmcnt(0)
	s_barrier
	s_cmp_gt_u32 s86, 2
	s_cbranch_scc1 .Ltp_done
	v_readlane_b32 s5, v253, 0
	s_sub_u32 s5, s5, 0x60
	s_cbranch_scc1 .Ltp_done
	s_cmp_gt_u32 s5, 0x9f
	s_cbranch_scc1 .Ltp_done
	s_mov_b64 exec, -1
	s_mov_b32 s20, s5
	s_lshr_b32 s6, s5, 2
	s_and_b32 s5, s5, 3
	s_add_i32 s7, s86, 1
	s_mul_i32 s8, s7, 0x5600000
	s_mul_i32 s9, s5, 0x1580000
	s_add_u32 s8, s8, s9
	s_lshl_b32 s9, s6, 9
	s_add_u32 s8, s8, s9
	v_readlane_b32 s0, v253, 23
	v_readlane_b32 s1, v253, 24
	s_add_u32 s0, s0, s8
	s_addc_u32 s1, s1, 0
	s_mul_i32 s8, s7, 0x2b00000
	s_add_u32 s8, s8, 0x4800000
	s_lshl_b32 s9, s6, 20
	s_add_u32 s8, s8, s9
	s_lshl_b32 s9, s5, 10
	s_add_u32 s8, s8, s9
	s_add_u32 s2, s72, s8
	s_addc_u32 s3, s73, 0
	v_readlane_b32 s16, v253, 29
	v_readlane_b32 s17, v253, 30
	s_mul_i32 s8, s7, 0x2b00000
	s_add_u32 s16, s16, s8
	s_addc_u32 s17, s17, 0
	s_mul_i32 s8, s7, 0x1580000
	s_add_u32 s8, s8, 0xf400000
	s_add_u32 s18, s72, s8
	s_addc_u32 s19, s73, 0
	v_mbcnt_lo_u32_b32 v114, -1, 0
	v_mbcnt_hi_u32_b32 v114, -1, v114
	v_readlane_b32 s5, v253, 37
	s_lshr_b32 s6, s5, 6
	v_bfe_u32 v115, v114, 5, 1
	v_bfe_u32 v116, v114, 3, 2
	v_and_b32_e32 v117, 3, v114
	v_bfe_u32 v118, v114, 2, 1
	v_lshlrev_b32_e32 v116, 7, v116
	v_lshl_add_u32 v116, v117, 5, v116
	v_lshl_add_u32 v116, v118, 4, v116
	v_mul_u32_u24_e32 v117, 0x5600, v115
	v_add_u32_e32 v117, v117, v116
	s_mul_i32 s7, s6, 0x56000
	v_add_u32_e32 v100, s7, v117
	v_add_u32_e32 v101, 0xac00, v100
	v_add_u32_e32 v102, 0xac00, v101
	v_add_u32_e32 v103, 0xac00, v102
	v_add_u32_e32 v104, 0xac00, v103
	v_add_u32_e32 v105, 0xac00, v104
	v_add_u32_e32 v106, 0xac00, v105
	v_add_u32_e32 v107, 0xac00, v106
	v_lshl_add_u32 v117, v115, 9, v116
	s_lshl_b32 s7, s6, 16
	v_add_u32_e32 v120, s7, v117
	v_add_u32_e32 v121, 0x2000, v120
	v_add_u32_e32 v122, 0x2000, v121
	v_add_u32_e32 v123, 0x2000, v122
	v_add_u32_e32 v124, 0x2000, v123
	v_add_u32_e32 v125, 0x2000, v124
	v_add_u32_e32 v126, 0x2000, v125
	v_add_u32_e32 v127, 0x2000, v126
	v_mul_u32_u24_e32 v108, 0x240, v114
	v_bfe_u32 v118, v114, 1, 2
	v_xor_b32_e32 v118, s6, v118
	v_lshl_add_u32 v108, v118, 4, v108
	v_lshrrev_b32_e32 v116, 3, v114
	s_lshl_b32 s7, s6, 3
	v_add_u32_e32 v116, s7, v116
	v_and_b32_e32 v117, 7, v114
	s_and_b32 s7, s6, 3
	v_xor_b32_e32 v118, s7, v117
	v_lshlrev_b32_e32 v117, 4, v117
	v_mul_u32_u24_e32 v109, 0x90, v116
	v_lshl_add_u32 v109, v118, 4, v109
	v_lshl_add_u32 v110, v116, 12, v117
	v_add_u32_e32 v111, 0x40000, v110
	v_add_u32_e32 v112, 0x40000, v111
	v_add_u32_e32 v113, 0x40000, v112
	v_mul_u32_u24_e32 v128, 0x2b00, v116
	v_add_u32_e32 v128, v128, v117
	v_add_u32_e32 v129, 0xac000, v128
	v_add_u32_e32 v130, 0xac000, v129
	v_add_u32_e32 v131, 0xac000, v130
	global_load_dwordx4 v[4:7], v100, s[0:1] nt
	global_load_dwordx4 v[8:11], v101, s[0:1] nt
	global_load_dwordx4 v[12:15], v102, s[0:1] nt
	global_load_dwordx4 v[16:19], v103, s[0:1] nt
	global_load_dwordx4 v[20:23], v104, s[0:1] nt
	global_load_dwordx4 v[24:27], v105, s[0:1] nt
	global_load_dwordx4 v[28:31], v106, s[0:1] nt
	global_load_dwordx4 v[32:35], v107, s[0:1] nt
	s_add_u32 s0, s0, 0x2b0000
	s_addc_u32 s1, s1, 0
	global_load_dwordx4 v[36:39], v100, s[0:1] nt
	global_load_dwordx4 v[40:43], v101, s[0:1] nt
	global_load_dwordx4 v[44:47], v102, s[0:1] nt
	global_load_dwordx4 v[48:51], v103, s[0:1] nt
	global_load_dwordx4 v[52:55], v104, s[0:1] nt
	global_load_dwordx4 v[56:59], v105, s[0:1] nt
	global_load_dwordx4 v[60:63], v106, s[0:1] nt
	global_load_dwordx4 v[64:67], v107, s[0:1] nt
	s_add_u32 s0, s0, 0x2b0000
	s_addc_u32 s1, s1, 0
	s_waitcnt vmcnt(8)
	v_cvt_pkrtz_f16_f32 v68, v4, v8
	v_cvt_pkrtz_f16_f32 v69, v12, v16
	v_cvt_pkrtz_f16_f32 v70, v20, v24
	v_cvt_pkrtz_f16_f32 v71, v28, v32
	ds_write_b128 v108, v[68:71] offset:0
	v_cvt_pkrtz_f16_f32 v72, v5, v9
	v_cvt_pkrtz_f16_f32 v73, v13, v17
	v_cvt_pkrtz_f16_f32 v74, v21, v25
	v_cvt_pkrtz_f16_f32 v75, v29, v33
	ds_write_b128 v108, v[72:75] offset:144
	v_cvt_pkrtz_f16_f32 v76, v6, v10
	v_cvt_pkrtz_f16_f32 v77, v14, v18
	v_cvt_pkrtz_f16_f32 v78, v22, v26
	v_cvt_pkrtz_f16_f32 v79, v30, v34
	ds_write_b128 v108, v[76:79] offset:288
	v_cvt_pkrtz_f16_f32 v80, v7, v11
	v_cvt_pkrtz_f16_f32 v81, v15, v19
	v_cvt_pkrtz_f16_f32 v82, v23, v27
	v_cvt_pkrtz_f16_f32 v83, v31, v35
	ds_write_b128 v108, v[80:83] offset:432
	s_waitcnt lgkmcnt(0)
	s_barrier
	ds_read_b128 v[84:87], v109 offset:0
	ds_read_b128 v[88:91], v109 offset:9216
	ds_read_b128 v[92:95], v109 offset:18432
	ds_read_b128 v[96:99], v109 offset:27648
	s_waitcnt lgkmcnt(3)
	global_store_dwordx4 v110, v[84:87], s[2:3] nt
	s_waitcnt lgkmcnt(2)
	global_store_dwordx4 v111, v[88:91], s[2:3] nt
	s_waitcnt lgkmcnt(1)
	global_store_dwordx4 v112, v[92:95], s[2:3] nt
	s_waitcnt lgkmcnt(0)
	global_store_dwordx4 v113, v[96:99], s[2:3] nt
	s_add_u32 s2, s2, 0x80
	s_addc_u32 s3, s3, 0
	global_load_dwordx4 v[4:7], v100, s[0:1] nt
	global_load_dwordx4 v[8:11], v101, s[0:1] nt
	global_load_dwordx4 v[12:15], v102, s[0:1] nt
	global_load_dwordx4 v[16:19], v103, s[0:1] nt
	global_load_dwordx4 v[20:23], v104, s[0:1] nt
	global_load_dwordx4 v[24:27], v105, s[0:1] nt
	global_load_dwordx4 v[28:31], v106, s[0:1] nt
	global_load_dwordx4 v[32:35], v107, s[0:1] nt
	s_add_u32 s0, s0, 0x2b0000
	s_addc_u32 s1, s1, 0
	s_waitcnt vmcnt(12)
	v_cvt_pkrtz_f16_f32 v68, v36, v40
	v_cvt_pkrtz_f16_f32 v69, v44, v48
	v_cvt_pkrtz_f16_f32 v70, v52, v56
	v_cvt_pkrtz_f16_f32 v71, v60, v64
	ds_write_b128 v108, v[68:71] offset:36864
	v_cvt_pkrtz_f16_f32 v72, v37, v41
	v_cvt_pkrtz_f16_f32 v73, v45, v49
	v_cvt_pkrtz_f16_f32 v74, v53, v57
	v_cvt_pkrtz_f16_f32 v75, v61, v65
	ds_write_b128 v108, v[72:75] offset:37008
	v_cvt_pkrtz_f16_f32 v76, v38, v42
	v_cvt_pkrtz_f16_f32 v77, v46, v50
	v_cvt_pkrtz_f16_f32 v78, v54, v58
	v_cvt_pkrtz_f16_f32 v79, v62, v66
	ds_write_b128 v108, v[76:79] offset:37152
	v_cvt_pkrtz_f16_f32 v80, v39, v43
	v_cvt_pkrtz_f16_f32 v81, v47, v51
	v_cvt_pkrtz_f16_f32 v82, v55, v59
	v_cvt_pkrtz_f16_f32 v83, v63, v67
	ds_write_b128 v108, v[80:83] offset:37296
	s_waitcnt lgkmcnt(0)
	s_barrier
; #define LAS __attribute__((address_space(3)))
; __device__ __forceinline__ unsigned cvt_pk_bf16(float lo, float hi) { return __builtin_bit_cast(unsigned, __builtin_amdgcn_cvt_pkrtz(lo, hi)); }
; #define bx (opaque_bx())
; __device__ __forceinline__ void phase_prep(int wid_s, const Args& a, unsigned char* shm) {
;     ...
;         while (t < PT_TOTAL) {
;             { const int w = tid >> 6, s4 = tid & 63;
; #pragma unroll
;               for (int q = 0; q < 4; ++q) { const u32x4 pc = {cvt_pk_bf16(r[0][q], r[1][q]), cvt_pk_bf16(r[2][q], r[3][q]), cvt_pk_bf16(r[4][q], r[5][q]), cvt_pk_bf16(r[6][q], r[7][q])};
;                   *(LAS u32x4*)(Lp + (4 * s4 + q) * 36 + 4 * w) = pc; } }
;             __syncthreads();
;             const PrepTask C = T; ++j; const int tn = ((j >> 2) * G + bx) * 4 + (j & 3);
;             if (tn < PT_TOTAL) { T = prep_decode(a, tn); prep_load(T, r, tid); }
; #pragma unroll
;             for (int q = 0; q < 4; ++q) { const int row = q * 64 + (tid >> 3), pc = tid & 7;
;                 const u32x4 v = *(const LAS u32x4*)(Lp + row * 36 + 4 * pc);
;                 *(u32x4*)(C.dst + (size_t)(256 * C.pn + row) * C.K + C.k0 + 8 * pc) = v; }
;             __syncthreads();
;             t = tn;
	ds_read_b128 v[84:87], v109 offset:36864
	ds_read_b128 v[88:91], v109 offset:46080
	ds_read_b128 v[92:95], v109 offset:55296
	ds_read_b128 v[96:99], v109 offset:64512
	s_waitcnt lgkmcnt(3)
	global_store_dwordx4 v110, v[84:87], s[2:3] nt
	s_waitcnt lgkmcnt(2)
	global_store_dwordx4 v111, v[88:91], s[2:3] nt
	s_waitcnt lgkmcnt(1)
	global_store_dwordx4 v112, v[92:95], s[2:3] nt
	s_waitcnt lgkmcnt(0)
	global_store_dwordx4 v113, v[96:99], s[2:3] nt
	s_add_u32 s2, s2, 0x80
	s_addc_u32 s3, s3, 0
	global_load_dwordx4 v[36:39], v100, s[0:1] nt
	global_load_dwordx4 v[40:43], v101, s[0:1] nt
	global_load_dwordx4 v[44:47], v102, s[0:1] nt
	global_load_dwordx4 v[48:51], v103, s[0:1] nt
	global_load_dwordx4 v[52:55], v104, s[0:1] nt
	global_load_dwordx4 v[56:59], v105, s[0:1] nt
	global_load_dwordx4 v[60:63], v106, s[0:1] nt
	global_load_dwordx4 v[64:67], v107, s[0:1] nt
	s_add_u32 s0, s0, 0x2b0000
	s_addc_u32 s1, s1, 0
	s_waitcnt vmcnt(12)
	v_cvt_pkrtz_f16_f32 v68, v4, v8
	v_cvt_pkrtz_f16_f32 v69, v12, v16
	v_cvt_pkrtz_f16_f32 v70, v20, v24
	v_cvt_pkrtz_f16_f32 v71, v28, v32
	ds_write_b128 v108, v[68:71] offset:0
	v_cvt_pkrtz_f16_f32 v72, v5, v9
	v_cvt_pkrtz_f16_f32 v73, v13, v17
	v_cvt_pkrtz_f16_f32 v74, v21, v25
	v_cvt_pkrtz_f16_f32 v75, v29, v33
	ds_write_b128 v108, v[72:75] offset:144
	v_cvt_pkrtz_f16_f32 v76, v6, v10
	v_cvt_pkrtz_f16_f32 v77, v14, v18
	v_cvt_pkrtz_f16_f32 v78, v22, v26
	v_cvt_pkrtz_f16_f32 v79, v30, v34
	ds_write_b128 v108, v[76:79] offset:288
	v_cvt_pkrtz_f16_f32 v80, v7, v11
	v_cvt_pkrtz_f16_f32 v81, v15, v19
	v_cvt_pkrtz_f16_f32 v82, v23, v27
	v_cvt_pkrtz_f16_f32 v83, v31, v35
	ds_write_b128 v108, v[80:83] offset:432
	s_waitcnt lgkmcnt(0)
	s_barrier
	ds_read_b128 v[84:87], v109 offset:0
	ds_read_b128 v[88:91], v109 offset:9216
	ds_read_b128 v[92:95], v109 offset:18432
	ds_read_b128 v[96:99], v109 offset:27648
	s_waitcnt lgkmcnt(3)
	global_store_dwordx4 v110, v[84:87], s[2:3] nt
	s_waitcnt lgkmcnt(2)
	global_store_dwordx4 v111, v[88:91], s[2:3] nt
	s_waitcnt lgkmcnt(1)
	global_store_dwordx4 v112, v[92:95], s[2:3] nt
	s_waitcnt lgkmcnt(0)
	global_store_dwordx4 v113, v[96:99], s[2:3] nt
	s_add_u32 s2, s2, 0x80
	s_addc_u32 s3, s3, 0
	global_load_dwordx4 v[4:7], v100, s[0:1] nt
	global_load_dwordx4 v[8:11], v101, s[0:1] nt
	global_load_dwordx4 v[12:15], v102, s[0:1] nt
	global_load_dwordx4 v[16:19], v103, s[0:1] nt
	global_load_dwordx4 v[20:23], v104, s[0:1] nt
	global_load_dwordx4 v[24:27], v105, s[0:1] nt
	global_load_dwordx4 v[28:31], v106, s[0:1] nt
	global_load_dwordx4 v[32:35], v107, s[0:1] nt
	s_add_u32 s0, s0, 0x2b0000
	s_addc_u32 s1, s1, 0
	s_waitcnt vmcnt(12)
	v_cvt_pkrtz_f16_f32 v68, v36, v40
	v_cvt_pkrtz_f16_f32 v69, v44, v48
	v_cvt_pkrtz_f16_f32 v70, v52, v56
	v_cvt_pkrtz_f16_f32 v71, v60, v64
	ds_write_b128 v108, v[68:71] offset:36864
	v_cvt_pkrtz_f16_f32 v72, v37, v41
	v_cvt_pkrtz_f16_f32 v73, v45, v49
	v_cvt_pkrtz_f16_f32 v74, v53, v57
	v_cvt_pkrtz_f16_f32 v75, v61, v65
	ds_write_b128 v108, v[72:75] offset:37008
	v_cvt_pkrtz_f16_f32 v76, v38, v42
	v_cvt_pkrtz_f16_f32 v77, v46, v50
	v_cvt_pkrtz_f16_f32 v78, v54, v58
	v_cvt_pkrtz_f16_f32 v79, v62, v66
	ds_write_b128 v108, v[76:79] offset:37152
	v_cvt_pkrtz_f16_f32 v80, v39, v43
	v_cvt_pkrtz_f16_f32 v81, v47, v51
	v_cvt_pkrtz_f16_f32 v82, v55, v59
	v_cvt_pkrtz_f16_f32 v83, v63, v67
	ds_write_b128 v108, v[80:83] offset:37296
	s_waitcnt lgkmcnt(0)
	s_barrier
	ds_read_b128 v[84:87], v109 offset:36864
	ds_read_b128 v[88:91], v109 offset:46080
	ds_read_b128 v[92:95], v109 offset:55296
	ds_read_b128 v[96:99], v109 offset:64512
	s_waitcnt lgkmcnt(3)
	global_store_dwordx4 v110, v[84:87], s[2:3] nt
	s_waitcnt lgkmcnt(2)
	global_store_dwordx4 v111, v[88:91], s[2:3] nt
	s_waitcnt lgkmcnt(1)
	global_store_dwordx4 v112, v[92:95], s[2:3] nt
	s_waitcnt lgkmcnt(0)
	global_store_dwordx4 v113, v[96:99], s[2:3] nt
	s_add_u32 s2, s2, 0x80
	s_addc_u32 s3, s3, 0
	global_load_dwordx4 v[36:39], v100, s[0:1] nt
	global_load_dwordx4 v[40:43], v101, s[0:1] nt
	global_load_dwordx4 v[44:47], v102, s[0:1] nt
	global_load_dwordx4 v[48:51], v103, s[0:1] nt
	global_load_dwordx4 v[52:55], v104, s[0:1] nt
	global_load_dwordx4 v[56:59], v105, s[0:1] nt
	global_load_dwordx4 v[60:63], v106, s[0:1] nt
	global_load_dwordx4 v[64:67], v107, s[0:1] nt
	s_add_u32 s0, s0, 0x2b0000
	s_addc_u32 s1, s1, 0
	s_waitcnt vmcnt(12)
	v_cvt_pkrtz_f16_f32 v68, v4, v8
	v_cvt_pkrtz_f16_f32 v69, v12, v16
	v_cvt_pkrtz_f16_f32 v70, v20, v24
	v_cvt_pkrtz_f16_f32 v71, v28, v32
	ds_write_b128 v108, v[68:71] offset:0
	v_cvt_pkrtz_f16_f32 v72, v5, v9
	v_cvt_pkrtz_f16_f32 v73, v13, v17
	v_cvt_pkrtz_f16_f32 v74, v21, v25
	v_cvt_pkrtz_f16_f32 v75, v29, v33
	ds_write_b128 v108, v[72:75] offset:144
	v_cvt_pkrtz_f16_f32 v76, v6, v10
	v_cvt_pkrtz_f16_f32 v77, v14, v18
	v_cvt_pkrtz_f16_f32 v78, v22, v26
	v_cvt_pkrtz_f16_f32 v79, v30, v34
	ds_write_b128 v108, v[76:79] offset:288
	v_cvt_pkrtz_f16_f32 v80, v7, v11
	v_cvt_pkrtz_f16_f32 v81, v15, v19
	v_cvt_pkrtz_f16_f32 v82, v23, v27
	v_cvt_pkrtz_f16_f32 v83, v31, v35
	ds_write_b128 v108, v[80:83] offset:432
	s_waitcnt lgkmcnt(0)
	s_barrier
; #define LAS __attribute__((address_space(3)))
; __device__ __forceinline__ unsigned cvt_pk_bf16(float lo, float hi) { return __builtin_bit_cast(unsigned, __builtin_amdgcn_cvt_pkrtz(lo, hi)); }
; #define bx (opaque_bx())
; #define ws (opaque_base(a.ws))
; __device__ __forceinline__ PrepTask prep_decode(const Args& a, int t) {
;     ...
;     else if ((r -= PT_UP) < PT_DN) { T.src = a.w_down + (size_t)l * DFF * DM; T.dst = (bf16_t*)(a.ws + WS_WDN + l * SZ_WDN); T.K = DFF; T.Nnat = DM; T.kind = KIND_STD; nt = 8; }
;     else { r -= PT_DN; T.src = a.glu_w + (size_t)l * 512 * 1024; T.dst = (bf16_t*)(a.ws + WS_WGLU + l * SZ_WGLU); T.K = 512; T.Nnat = 1024; T.kind = KIND_GLU; nt = 4; }
;     (void)nt; const int KT = T.K / 64; T.pn = r / KT; T.k0 = (r % KT) * 64; return T;
; __device__ __forceinline__ void phase_prep(int wid_s, const Args& a, unsigned char* shm) {
;     ...
;         while (t < PT_TOTAL) {
;             { const int w = tid >> 6, s4 = tid & 63;
; #pragma unroll
;               for (int q = 0; q < 4; ++q) { const u32x4 pc = {cvt_pk_bf16(r[0][q], r[1][q]), cvt_pk_bf16(r[2][q], r[3][q]), cvt_pk_bf16(r[4][q], r[5][q]), cvt_pk_bf16(r[6][q], r[7][q])};
;                   *(LAS u32x4*)(Lp + (4 * s4 + q) * 36 + 4 * w) = pc; } }
;             __syncthreads();
;             const PrepTask C = T; ++j; const int tn = ((j >> 2) * G + bx) * 4 + (j & 3);
;             if (tn < PT_TOTAL) { T = prep_decode(a, tn); prep_load(T, r, tid); }
; #pragma unroll
;             for (int q = 0; q < 4; ++q) { const int row = q * 64 + (tid >> 3), pc = tid & 7;
;                 const u32x4 v = *(const LAS u32x4*)(Lp + row * 36 + 4 * pc);
;                 *(u32x4*)(C.dst + (size_t)(256 * C.pn + row) * C.K + C.k0 + 8 * pc) = v; }
;             __syncthreads();
;             t = tn;
	ds_read_b128 v[84:87], v109 offset:0
	ds_read_b128 v[88:91], v109 offset:9216
	ds_read_b128 v[92:95], v109 offset:18432
	ds_read_b128 v[96:99], v109 offset:27648
	s_waitcnt lgkmcnt(3)
	global_store_dwordx4 v110, v[84:87], s[2:3] nt
	s_waitcnt lgkmcnt(2)
	global_store_dwordx4 v111, v[88:91], s[2:3] nt
	s_waitcnt lgkmcnt(1)
	global_store_dwordx4 v112, v[92:95], s[2:3] nt
	s_waitcnt lgkmcnt(0)
	global_store_dwordx4 v113, v[96:99], s[2:3] nt
	s_add_u32 s2, s2, 0x80
	s_addc_u32 s3, s3, 0
	global_load_dwordx4 v[4:7], v100, s[0:1] nt
	global_load_dwordx4 v[8:11], v101, s[0:1] nt
	global_load_dwordx4 v[12:15], v102, s[0:1] nt
	global_load_dwordx4 v[16:19], v103, s[0:1] nt
	global_load_dwordx4 v[20:23], v104, s[0:1] nt
	global_load_dwordx4 v[24:27], v105, s[0:1] nt
	global_load_dwordx4 v[28:31], v106, s[0:1] nt
	global_load_dwordx4 v[32:35], v107, s[0:1] nt
	s_add_u32 s0, s0, 0x2b0000
	s_addc_u32 s1, s1, 0
	s_waitcnt vmcnt(12)
	v_cvt_pkrtz_f16_f32 v68, v36, v40
	v_cvt_pkrtz_f16_f32 v69, v44, v48
	v_cvt_pkrtz_f16_f32 v70, v52, v56
	v_cvt_pkrtz_f16_f32 v71, v60, v64
	ds_write_b128 v108, v[68:71] offset:36864
	v_cvt_pkrtz_f16_f32 v72, v37, v41
	v_cvt_pkrtz_f16_f32 v73, v45, v49
	v_cvt_pkrtz_f16_f32 v74, v53, v57
	v_cvt_pkrtz_f16_f32 v75, v61, v65
	ds_write_b128 v108, v[72:75] offset:37008
	v_cvt_pkrtz_f16_f32 v76, v38, v42
	v_cvt_pkrtz_f16_f32 v77, v46, v50
	v_cvt_pkrtz_f16_f32 v78, v54, v58
	v_cvt_pkrtz_f16_f32 v79, v62, v66
	ds_write_b128 v108, v[76:79] offset:37152
	v_cvt_pkrtz_f16_f32 v80, v39, v43
	v_cvt_pkrtz_f16_f32 v81, v47, v51
	v_cvt_pkrtz_f16_f32 v82, v55, v59
	v_cvt_pkrtz_f16_f32 v83, v63, v67
	ds_write_b128 v108, v[80:83] offset:37296
	s_waitcnt lgkmcnt(0)
	s_barrier
	ds_read_b128 v[84:87], v109 offset:36864
	ds_read_b128 v[88:91], v109 offset:46080
	ds_read_b128 v[92:95], v109 offset:55296
	ds_read_b128 v[96:99], v109 offset:64512
	s_waitcnt lgkmcnt(3)
	global_store_dwordx4 v110, v[84:87], s[2:3] nt
	s_waitcnt lgkmcnt(2)
	global_store_dwordx4 v111, v[88:91], s[2:3] nt
	s_waitcnt lgkmcnt(1)
	global_store_dwordx4 v112, v[92:95], s[2:3] nt
	s_waitcnt lgkmcnt(0)
	global_store_dwordx4 v113, v[96:99], s[2:3] nt
	s_add_u32 s2, s2, 0x80
	s_addc_u32 s3, s3, 0
	global_load_dwordx4 v[36:39], v100, s[0:1] nt
	global_load_dwordx4 v[40:43], v101, s[0:1] nt
	global_load_dwordx4 v[44:47], v102, s[0:1] nt
	global_load_dwordx4 v[48:51], v103, s[0:1] nt
	global_load_dwordx4 v[52:55], v104, s[0:1] nt
	global_load_dwordx4 v[56:59], v105, s[0:1] nt
	global_load_dwordx4 v[60:63], v106, s[0:1] nt
	global_load_dwordx4 v[64:67], v107, s[0:1] nt
	s_add_u32 s0, s0, 0x2b0000
	s_addc_u32 s1, s1, 0
	s_waitcnt vmcnt(12)
	v_cvt_pkrtz_f16_f32 v68, v4, v8
	v_cvt_pkrtz_f16_f32 v69, v12, v16
	v_cvt_pkrtz_f16_f32 v70, v20, v24
	v_cvt_pkrtz_f16_f32 v71, v28, v32
	ds_write_b128 v108, v[68:71] offset:0
	v_cvt_pkrtz_f16_f32 v72, v5, v9
	v_cvt_pkrtz_f16_f32 v73, v13, v17
	v_cvt_pkrtz_f16_f32 v74, v21, v25
	v_cvt_pkrtz_f16_f32 v75, v29, v33
	ds_write_b128 v108, v[72:75] offset:144
	v_cvt_pkrtz_f16_f32 v76, v6, v10
	v_cvt_pkrtz_f16_f32 v77, v14, v18
	v_cvt_pkrtz_f16_f32 v78, v22, v26
	v_cvt_pkrtz_f16_f32 v79, v30, v34
	ds_write_b128 v108, v[76:79] offset:288
	v_cvt_pkrtz_f16_f32 v80, v7, v11
	v_cvt_pkrtz_f16_f32 v81, v15, v19
	v_cvt_pkrtz_f16_f32 v82, v23, v27
	v_cvt_pkrtz_f16_f32 v83, v31, v35
	ds_write_b128 v108, v[80:83] offset:432
	s_waitcnt lgkmcnt(0)
	s_barrier
	ds_read_b128 v[84:87], v109 offset:0
	ds_read_b128 v[88:91], v109 offset:9216
	ds_read_b128 v[92:95], v109 offset:18432
	ds_read_b128 v[96:99], v109 offset:27648
	s_waitcnt lgkmcnt(3)
	global_store_dwordx4 v110, v[84:87], s[2:3] nt
	s_waitcnt lgkmcnt(2)
	global_store_dwordx4 v111, v[88:91], s[2:3] nt
	s_waitcnt lgkmcnt(1)
	global_store_dwordx4 v112, v[92:95], s[2:3] nt
	s_waitcnt lgkmcnt(0)
	global_store_dwordx4 v113, v[96:99], s[2:3] nt
	s_add_u32 s2, s2, 0x80
	s_addc_u32 s3, s3, 0
	s_lshl_b32 s8, s20, 2
	s_mul_i32 s9, s8, 0x2fb
	s_lshr_b32 s9, s9, 16
	s_mul_i32 s14, s9, 0x56
	s_sub_u32 s8, s8, s14
	s_lshl_b32 s14, s8, 19
	s_lshl_b32 s15, s9, 10
	s_add_u32 s14, s14, s15
	s_add_u32 s22, s16, s14
	s_addc_u32 s23, s17, 0
	s_mul_i32 s14, s9, 0x2b0000
	s_lshl_b32 s15, s8, 7
	s_add_u32 s14, s14, s15
	s_add_u32 s24, s18, s14
	s_addc_u32 s25, s19, 0
	global_load_dwordx4 v[4:7], v120, s[22:23] nt
	global_load_dwordx4 v[8:11], v121, s[22:23] nt
	global_load_dwordx4 v[12:15], v122, s[22:23] nt
	global_load_dwordx4 v[16:19], v123, s[22:23] nt
	global_load_dwordx4 v[20:23], v124, s[22:23] nt
	global_load_dwordx4 v[24:27], v125, s[22:23] nt
	global_load_dwordx4 v[28:31], v126, s[22:23] nt
	global_load_dwordx4 v[32:35], v127, s[22:23] nt
	s_waitcnt vmcnt(12)
	v_cvt_pkrtz_f16_f32 v68, v36, v40
	v_cvt_pkrtz_f16_f32 v69, v44, v48
	v_cvt_pkrtz_f16_f32 v70, v52, v56
	v_cvt_pkrtz_f16_f32 v71, v60, v64
	ds_write_b128 v108, v[68:71] offset:36864
	v_cvt_pkrtz_f16_f32 v72, v37, v41
	v_cvt_pkrtz_f16_f32 v73, v45, v49
	v_cvt_pkrtz_f16_f32 v74, v53, v57
	v_cvt_pkrtz_f16_f32 v75, v61, v65
	ds_write_b128 v108, v[72:75] offset:37008
	v_cvt_pkrtz_f16_f32 v76, v38, v42
	v_cvt_pkrtz_f16_f32 v77, v46, v50
	v_cvt_pkrtz_f16_f32 v78, v54, v58
	v_cvt_pkrtz_f16_f32 v79, v62, v66
	ds_write_b128 v108, v[76:79] offset:37152
	v_cvt_pkrtz_f16_f32 v80, v39, v43
	v_cvt_pkrtz_f16_f32 v81, v47, v51
	v_cvt_pkrtz_f16_f32 v82, v55, v59
	v_cvt_pkrtz_f16_f32 v83, v63, v67
	ds_write_b128 v108, v[80:83] offset:37296
	s_waitcnt lgkmcnt(0)
	s_barrier
; #define LAS __attribute__((address_space(3)))
; __device__ __forceinline__ unsigned cvt_pk_bf16(float lo, float hi) { return __builtin_bit_cast(unsigned, __builtin_amdgcn_cvt_pkrtz(lo, hi)); }
; #define bx (opaque_bx())
; #define ws (opaque_base(a.ws))
; __device__ __forceinline__ PrepTask prep_decode(const Args& a, int t) {
;     ...
;     else if ((r -= PT_UP) < PT_DN) { T.src = a.w_down + (size_t)l * DFF * DM; T.dst = (bf16_t*)(a.ws + WS_WDN + l * SZ_WDN); T.K = DFF; T.Nnat = DM; T.kind = KIND_STD; nt = 8; }
;     else { r -= PT_DN; T.src = a.glu_w + (size_t)l * 512 * 1024; T.dst = (bf16_t*)(a.ws + WS_WGLU + l * SZ_WGLU); T.K = 512; T.Nnat = 1024; T.kind = KIND_GLU; nt = 4; }
;     (void)nt; const int KT = T.K / 64; T.pn = r / KT; T.k0 = (r % KT) * 64; return T;
; __device__ __forceinline__ void phase_prep(int wid_s, const Args& a, unsigned char* shm) {
;     ...
;         while (t < PT_TOTAL) {
;             { const int w = tid >> 6, s4 = tid & 63;
; #pragma unroll
;               for (int q = 0; q < 4; ++q) { const u32x4 pc = {cvt_pk_bf16(r[0][q], r[1][q]), cvt_pk_bf16(r[2][q], r[3][q]), cvt_pk_bf16(r[4][q], r[5][q]), cvt_pk_bf16(r[6][q], r[7][q])};
;                   *(LAS u32x4*)(Lp + (4 * s4 + q) * 36 + 4 * w) = pc; } }
;             __syncthreads();
;             const PrepTask C = T; ++j; const int tn = ((j >> 2) * G + bx) * 4 + (j & 3);
;             if (tn < PT_TOTAL) { T = prep_decode(a, tn); prep_load(T, r, tid); }
; #pragma unroll
;             for (int q = 0; q < 4; ++q) { const int row = q * 64 + (tid >> 3), pc = tid & 7;
;                 const u32x4 v = *(const LAS u32x4*)(Lp + row * 36 + 4 * pc);
;                 *(u32x4*)(C.dst + (size_t)(256 * C.pn + row) * C.K + C.k0 + 8 * pc) = v; }
;             __syncthreads();
;             t = tn;
	ds_read_b128 v[84:87], v109 offset:36864
	ds_read_b128 v[88:91], v109 offset:46080
	ds_read_b128 v[92:95], v109 offset:55296
	ds_read_b128 v[96:99], v109 offset:64512
	s_waitcnt lgkmcnt(3)
	global_store_dwordx4 v110, v[84:87], s[2:3] nt
	s_waitcnt lgkmcnt(2)
	global_store_dwordx4 v111, v[88:91], s[2:3] nt
	s_waitcnt lgkmcnt(1)
	global_store_dwordx4 v112, v[92:95], s[2:3] nt
	s_waitcnt lgkmcnt(0)
	global_store_dwordx4 v113, v[96:99], s[2:3] nt
	s_add_u32 s2, s2, 0x80
	s_addc_u32 s3, s3, 0
	s_lshl_b32 s8, s20, 2
	s_add_u32 s8, s8, 1
	s_mul_i32 s9, s8, 0x2fb
	s_lshr_b32 s9, s9, 16
	s_mul_i32 s14, s9, 0x56
	s_sub_u32 s8, s8, s14
	s_lshl_b32 s14, s8, 19
	s_lshl_b32 s15, s9, 10
	s_add_u32 s14, s14, s15
	s_add_u32 s22, s16, s14
	s_addc_u32 s23, s17, 0
	s_mul_i32 s14, s9, 0x2b0000
	s_lshl_b32 s15, s8, 7
	s_add_u32 s14, s14, s15
	s_add_u32 s26, s18, s14
	s_addc_u32 s27, s19, 0
	global_load_dwordx4 v[36:39], v120, s[22:23] nt
	global_load_dwordx4 v[40:43], v121, s[22:23] nt
	global_load_dwordx4 v[44:47], v122, s[22:23] nt
	global_load_dwordx4 v[48:51], v123, s[22:23] nt
	global_load_dwordx4 v[52:55], v124, s[22:23] nt
	global_load_dwordx4 v[56:59], v125, s[22:23] nt
	global_load_dwordx4 v[60:63], v126, s[22:23] nt
	global_load_dwordx4 v[64:67], v127, s[22:23] nt
	s_waitcnt vmcnt(12)
	v_cvt_pkrtz_f16_f32 v68, v4, v8
	v_cvt_pkrtz_f16_f32 v69, v12, v16
	v_cvt_pkrtz_f16_f32 v70, v20, v24
	v_cvt_pkrtz_f16_f32 v71, v28, v32
	ds_write_b128 v108, v[68:71] offset:0
	v_cvt_pkrtz_f16_f32 v72, v5, v9
	v_cvt_pkrtz_f16_f32 v73, v13, v17
	v_cvt_pkrtz_f16_f32 v74, v21, v25
	v_cvt_pkrtz_f16_f32 v75, v29, v33
	ds_write_b128 v108, v[72:75] offset:144
	v_cvt_pkrtz_f16_f32 v76, v6, v10
	v_cvt_pkrtz_f16_f32 v77, v14, v18
	v_cvt_pkrtz_f16_f32 v78, v22, v26
	v_cvt_pkrtz_f16_f32 v79, v30, v34
	ds_write_b128 v108, v[76:79] offset:288
	v_cvt_pkrtz_f16_f32 v80, v7, v11
	v_cvt_pkrtz_f16_f32 v81, v15, v19
	v_cvt_pkrtz_f16_f32 v82, v23, v27
	v_cvt_pkrtz_f16_f32 v83, v31, v35
	ds_write_b128 v108, v[80:83] offset:432
	s_waitcnt lgkmcnt(0)
	s_barrier
	ds_read_b128 v[84:87], v109 offset:0
	ds_read_b128 v[88:91], v109 offset:9216
	ds_read_b128 v[92:95], v109 offset:18432
	ds_read_b128 v[96:99], v109 offset:27648
	s_waitcnt lgkmcnt(3)
	global_store_dwordx4 v128, v[84:87], s[24:25] nt
	s_waitcnt lgkmcnt(2)
	global_store_dwordx4 v129, v[88:91], s[24:25] nt
	s_waitcnt lgkmcnt(1)
	global_store_dwordx4 v130, v[92:95], s[24:25] nt
	s_waitcnt lgkmcnt(0)
	global_store_dwordx4 v131, v[96:99], s[24:25] nt
	s_lshl_b32 s8, s20, 2
	s_add_u32 s8, s8, 2
	s_mul_i32 s9, s8, 0x2fb
	s_lshr_b32 s9, s9, 16
	s_mul_i32 s14, s9, 0x56
	s_sub_u32 s8, s8, s14
	s_lshl_b32 s14, s8, 19
	s_lshl_b32 s15, s9, 10
	s_add_u32 s14, s14, s15
	s_add_u32 s22, s16, s14
	s_addc_u32 s23, s17, 0
	s_mul_i32 s14, s9, 0x2b0000
	s_lshl_b32 s15, s8, 7
	s_add_u32 s14, s14, s15
	s_add_u32 s24, s18, s14
	s_addc_u32 s25, s19, 0
	global_load_dwordx4 v[4:7], v120, s[22:23] nt
	global_load_dwordx4 v[8:11], v121, s[22:23] nt
	global_load_dwordx4 v[12:15], v122, s[22:23] nt
	global_load_dwordx4 v[16:19], v123, s[22:23] nt
	global_load_dwordx4 v[20:23], v124, s[22:23] nt
	global_load_dwordx4 v[24:27], v125, s[22:23] nt
	global_load_dwordx4 v[28:31], v126, s[22:23] nt
	global_load_dwordx4 v[32:35], v127, s[22:23] nt
	s_waitcnt vmcnt(12)
	v_cvt_pkrtz_f16_f32 v68, v36, v40
	v_cvt_pkrtz_f16_f32 v69, v44, v48
	v_cvt_pkrtz_f16_f32 v70, v52, v56
	v_cvt_pkrtz_f16_f32 v71, v60, v64
	ds_write_b128 v108, v[68:71] offset:36864
	v_cvt_pkrtz_f16_f32 v72, v37, v41
	v_cvt_pkrtz_f16_f32 v73, v45, v49
	v_cvt_pkrtz_f16_f32 v74, v53, v57
	v_cvt_pkrtz_f16_f32 v75, v61, v65
	ds_write_b128 v108, v[72:75] offset:37008
	v_cvt_pkrtz_f16_f32 v76, v38, v42
	v_cvt_pkrtz_f16_f32 v77, v46, v50
	v_cvt_pkrtz_f16_f32 v78, v54, v58
	v_cvt_pkrtz_f16_f32 v79, v62, v66
	ds_write_b128 v108, v[76:79] offset:37152
	v_cvt_pkrtz_f16_f32 v80, v39, v43
	v_cvt_pkrtz_f16_f32 v81, v47, v51
	v_cvt_pkrtz_f16_f32 v82, v55, v59
	v_cvt_pkrtz_f16_f32 v83, v63, v67
	ds_write_b128 v108, v[80:83] offset:37296
	s_waitcnt lgkmcnt(0)
	s_barrier
; #define LAS __attribute__((address_space(3)))
; __device__ __forceinline__ unsigned cvt_pk_bf16(float lo, float hi) { return __builtin_bit_cast(unsigned, __builtin_amdgcn_cvt_pkrtz(lo, hi)); }
; #define bx (opaque_bx())
; __device__ __forceinline__ void phase_prep(int wid_s, const Args& a, unsigned char* shm) {
;     ...
;         while (t < PT_TOTAL) {
;             { const int w = tid >> 6, s4 = tid & 63;
; #pragma unroll
;               for (int q = 0; q < 4; ++q) { const u32x4 pc = {cvt_pk_bf16(r[0][q], r[1][q]), cvt_pk_bf16(r[2][q], r[3][q]), cvt_pk_bf16(r[4][q], r[5][q]), cvt_pk_bf16(r[6][q], r[7][q])};
;                   *(LAS u32x4*)(Lp + (4 * s4 + q) * 36 + 4 * w) = pc; } }
;             __syncthreads();
;             const PrepTask C = T; ++j; const int tn = ((j >> 2) * G + bx) * 4 + (j & 3);
;             if (tn < PT_TOTAL) { T = prep_decode(a, tn); prep_load(T, r, tid); }
; #pragma unroll
;             for (int q = 0; q < 4; ++q) { const int row = q * 64 + (tid >> 3), pc = tid & 7;
;                 const u32x4 v = *(const LAS u32x4*)(Lp + row * 36 + 4 * pc);
;                 *(u32x4*)(C.dst + (size_t)(256 * C.pn + row) * C.K + C.k0 + 8 * pc) = v; }
;             __syncthreads();
;             t = tn;
	ds_read_b128 v[84:87], v109 offset:36864
	ds_read_b128 v[88:91], v109 offset:46080
	ds_read_b128 v[92:95], v109 offset:55296
	ds_read_b128 v[96:99], v109 offset:64512
	s_waitcnt lgkmcnt(3)
	global_store_dwordx4 v128, v[84:87], s[26:27] nt
	s_waitcnt lgkmcnt(2)
	global_store_dwordx4 v129, v[88:91], s[26:27] nt
	s_waitcnt lgkmcnt(1)
	global_store_dwordx4 v130, v[92:95], s[26:27] nt
	s_waitcnt lgkmcnt(0)
	global_store_dwordx4 v131, v[96:99], s[26:27] nt
	s_lshl_b32 s8, s20, 2
	s_add_u32 s8, s8, 3
	s_mul_i32 s9, s8, 0x2fb
	s_lshr_b32 s9, s9, 16
	s_mul_i32 s14, s9, 0x56
	s_sub_u32 s8, s8, s14
	s_lshl_b32 s14, s8, 19
	s_lshl_b32 s15, s9, 10
	s_add_u32 s14, s14, s15
	s_add_u32 s22, s16, s14
	s_addc_u32 s23, s17, 0
	s_mul_i32 s14, s9, 0x2b0000
	s_lshl_b32 s15, s8, 7
	s_add_u32 s14, s14, s15
	s_add_u32 s26, s18, s14
	s_addc_u32 s27, s19, 0
	global_load_dwordx4 v[36:39], v120, s[22:23] nt
	global_load_dwordx4 v[40:43], v121, s[22:23] nt
	global_load_dwordx4 v[44:47], v122, s[22:23] nt
	global_load_dwordx4 v[48:51], v123, s[22:23] nt
	global_load_dwordx4 v[52:55], v124, s[22:23] nt
	global_load_dwordx4 v[56:59], v125, s[22:23] nt
	global_load_dwordx4 v[60:63], v126, s[22:23] nt
	global_load_dwordx4 v[64:67], v127, s[22:23] nt
	s_waitcnt vmcnt(12)
	v_cvt_pkrtz_f16_f32 v68, v4, v8
	v_cvt_pkrtz_f16_f32 v69, v12, v16
	v_cvt_pkrtz_f16_f32 v70, v20, v24
	v_cvt_pkrtz_f16_f32 v71, v28, v32
	ds_write_b128 v108, v[68:71] offset:0
	v_cvt_pkrtz_f16_f32 v72, v5, v9
	v_cvt_pkrtz_f16_f32 v73, v13, v17
	v_cvt_pkrtz_f16_f32 v74, v21, v25
	v_cvt_pkrtz_f16_f32 v75, v29, v33
	ds_write_b128 v108, v[72:75] offset:144
	v_cvt_pkrtz_f16_f32 v76, v6, v10
	v_cvt_pkrtz_f16_f32 v77, v14, v18
	v_cvt_pkrtz_f16_f32 v78, v22, v26
	v_cvt_pkrtz_f16_f32 v79, v30, v34
	ds_write_b128 v108, v[76:79] offset:288
	v_cvt_pkrtz_f16_f32 v80, v7, v11
	v_cvt_pkrtz_f16_f32 v81, v15, v19
	v_cvt_pkrtz_f16_f32 v82, v23, v27
	v_cvt_pkrtz_f16_f32 v83, v31, v35
	ds_write_b128 v108, v[80:83] offset:432
	s_waitcnt lgkmcnt(0)
	s_barrier
	ds_read_b128 v[84:87], v109 offset:0
	ds_read_b128 v[88:91], v109 offset:9216
	ds_read_b128 v[92:95], v109 offset:18432
	ds_read_b128 v[96:99], v109 offset:27648
	s_waitcnt lgkmcnt(3)
	global_store_dwordx4 v128, v[84:87], s[24:25] nt
	s_waitcnt lgkmcnt(2)
	global_store_dwordx4 v129, v[88:91], s[24:25] nt
	s_waitcnt lgkmcnt(1)
	global_store_dwordx4 v130, v[92:95], s[24:25] nt
	s_waitcnt lgkmcnt(0)
	global_store_dwordx4 v131, v[96:99], s[24:25] nt
	s_waitcnt vmcnt(4)
	v_cvt_pkrtz_f16_f32 v68, v36, v40
	v_cvt_pkrtz_f16_f32 v69, v44, v48
	v_cvt_pkrtz_f16_f32 v70, v52, v56
	v_cvt_pkrtz_f16_f32 v71, v60, v64
	ds_write_b128 v108, v[68:71] offset:36864
	v_cvt_pkrtz_f16_f32 v72, v37, v41
	v_cvt_pkrtz_f16_f32 v73, v45, v49
	v_cvt_pkrtz_f16_f32 v74, v53, v57
	v_cvt_pkrtz_f16_f32 v75, v61, v65
	ds_write_b128 v108, v[72:75] offset:37008
	v_cvt_pkrtz_f16_f32 v76, v38, v42
	v_cvt_pkrtz_f16_f32 v77, v46, v50
	v_cvt_pkrtz_f16_f32 v78, v54, v58
	v_cvt_pkrtz_f16_f32 v79, v62, v66
	ds_write_b128 v108, v[76:79] offset:37152
	v_cvt_pkrtz_f16_f32 v80, v39, v43
	v_cvt_pkrtz_f16_f32 v81, v47, v51
	v_cvt_pkrtz_f16_f32 v82, v55, v59
	v_cvt_pkrtz_f16_f32 v83, v63, v67
	ds_write_b128 v108, v[80:83] offset:37296
	s_waitcnt lgkmcnt(0)
	s_barrier
	ds_read_b128 v[84:87], v109 offset:36864
	ds_read_b128 v[88:91], v109 offset:46080
	ds_read_b128 v[92:95], v109 offset:55296
	ds_read_b128 v[96:99], v109 offset:64512
	s_waitcnt lgkmcnt(3)
	global_store_dwordx4 v128, v[84:87], s[26:27] nt
	s_waitcnt lgkmcnt(2)
	global_store_dwordx4 v129, v[88:91], s[26:27] nt
	s_waitcnt lgkmcnt(1)
	global_store_dwordx4 v130, v[92:95], s[26:27] nt
	s_waitcnt lgkmcnt(0)
	global_store_dwordx4 v131, v[96:99], s[26:27] nt
